# nt on scan-phase chunk-state loads and conv-mixer activation loads
# baseline (speedup 1.0000x reference)
; __device__ __forceinline__ float bf_lo(unsigned w) { return __uint_as_float(w << 16); }
; __device__ __forceinline__ float bf_hi(unsigned w) { return __uint_as_float(w & 0xffff0000u); }
; __global__ void __launch_bounds__(NTHR, 2) fwd_kernel(Args a) {
;     ...
;             for (int rc_ = 0; rc_ < REP_M1C; ++rc_) for (int item = gt; item < (MP / 16) * 256; item += NGT) {
;                 const int c4 = (item & 255) * 4, row0 = (item >> 8) * 16; const bool cont = (row0 & (SEQ - 1)) != 0; const bf16_t* up = (const bf16_t*)UC + (size_t)row0 * CONVD + c4; const f32x4 z = {0.f, 0.f, 0.f, 0.f};
;                 f32x4 u[18]; u32x2 bg[16];
;                 u32x2 ub[18]; ub[0] = cont ? *(const u32x2*)(up - 2 * CONVD) : (u32x2){0u, 0u}; ub[1] = cont ? *(const u32x2*)(up - CONVD) : (u32x2){0u, 0u};
; #pragma unroll
;                 for (int i = 0; i < 16; ++i) { ub[2 + i] = *(const u32x2*)(up + (size_t)i * CONVD); bg[i] = *(const u32x2*)(PR + (size_t)(row0 + i) * PRW + c4); }
;                 const f32x4 w0 = *(const f32x4*)(cw + c4), w1 = *(const f32x4*)(cw + CONVD + c4), w2v = *(const f32x4*)(cw + 2 * CONVD + c4);
; #pragma unroll
;                 for (int i = 0; i < 18; ++i) u[i] = (f32x4){bf_lo(ub[i].x), bf_hi(ub[i].x), bf_lo(ub[i].y), bf_hi(ub[i].y)};
.LBB0_370:
	s_or_b64 exec, exec, s[6:7]
	v_or_b32_e32 v104, 1, v96
	v_lshl_add_u64 v[4:5], s[34:35], 0, v[168:169]
	v_lshlrev_b64 v[6:7], 13, v[96:97]
	v_ashrrev_i32_e32 v105, 31, v104
	v_lshl_add_u64 v[6:7], v[4:5], 0, v[6:7]
	v_lshlrev_b64 v[8:9], 13, v[104:105]
	v_lshl_add_u64 v[8:9], v[4:5], 0, v[8:9]
	global_load_dwordx2 v[32:33], v[0:1], off nt
	global_load_dwordx2 v[128:129], v[6:7], off nt
	global_load_dwordx2 v[112:113], v[8:9], off nt
	global_load_dwordx2 v[34:35], v[0:1], off offset:2048 nt
	v_add_co_u32_e32 v6, vcc, s15, v0
	v_or_b32_e32 v100, 2, v96
	s_nop 0
	v_addc_co_u32_e32 v7, vcc, 0, v1, vcc
	v_ashrrev_i32_e32 v101, 31, v100
	v_or_b32_e32 v90, 3, v96
	v_or_b32_e32 v82, 4, v96
	v_add_co_u32_e32 v8, vcc, s59, v0
	v_lshlrev_b64 v[10:11], 13, v[100:101]
	v_ashrrev_i32_e32 v91, 31, v90
	v_ashrrev_i32_e32 v83, 31, v82
	v_addc_co_u32_e32 v9, vcc, 0, v1, vcc
	v_lshl_add_u64 v[10:11], v[4:5], 0, v[10:11]
	v_lshlrev_b64 v[12:13], 13, v[90:91]
	v_lshlrev_b64 v[14:15], 13, v[82:83]
	v_lshl_add_u64 v[12:13], v[4:5], 0, v[12:13]
	v_lshl_add_u64 v[14:15], v[4:5], 0, v[14:15]
	global_load_dwordx2 v[114:115], v[10:11], off nt
	global_load_dwordx2 v[106:107], v[12:13], off nt
	global_load_dwordx2 v[92:93], v[14:15], off nt
	global_load_dwordx2 v[36:37], v[6:7], off offset:2048 nt
	v_or_b32_e32 v74, 5, v96
	v_add_co_u32_e32 v10, vcc, s62, v0
	v_ashrrev_i32_e32 v75, 31, v74
	s_nop 0
	v_addc_co_u32_e32 v11, vcc, 0, v1, vcc
	v_or_b32_e32 v70, 6, v96
	v_or_b32_e32 v62, 7, v96
	v_lshlrev_b64 v[6:7], 13, v[74:75]
	v_add_co_u32_e32 v12, vcc, s60, v0
	v_ashrrev_i32_e32 v71, 31, v70
	v_ashrrev_i32_e32 v63, 31, v62
	v_lshl_add_u64 v[6:7], v[4:5], 0, v[6:7]
	v_addc_co_u32_e32 v13, vcc, 0, v1, vcc
	global_load_dwordx2 v[40:41], v[8:9], off offset:-4096 nt
	global_load_dwordx2 v[42:43], v[8:9], off nt
	global_load_dwordx2 v[46:47], v[8:9], off offset:2048 nt
	global_load_dwordx2 v[50:51], v[12:13], off offset:-4096 nt
	v_lshlrev_b64 v[8:9], 13, v[70:71]
	v_lshlrev_b64 v[14:15], 13, v[62:63]
	v_lshl_add_u64 v[8:9], v[4:5], 0, v[8:9]
	v_lshl_add_u64 v[14:15], v[4:5], 0, v[14:15]
	global_load_dwordx2 v[94:95], v[6:7], off nt
	global_load_dwordx2 v[84:85], v[8:9], off nt
	global_load_dwordx2 v[72:73], v[14:15], off nt
	global_load_dwordx2 v[56:57], v[10:11], off offset:2048 nt
	v_add_co_u32_e32 v10, vcc, s16, v0
	v_or_b32_e32 v54, 8, v96
	s_nop 0
	v_addc_co_u32_e32 v11, vcc, 0, v1, vcc
	global_load_dwordx2 v[58:59], v[12:13], off nt
	global_load_dwordx2 v[66:67], v[12:13], off offset:2048 nt
	v_add_co_u32_e32 v12, vcc, s61, v0
	v_or_b32_e32 v38, 10, v96
	v_ashrrev_i32_e32 v55, 31, v54
	v_or_b32_e32 v44, 9, v96
	v_addc_co_u32_e32 v13, vcc, 0, v1, vcc
	v_ashrrev_i32_e32 v39, 31, v38
	v_lshlrev_b64 v[6:7], 13, v[54:55]
	v_ashrrev_i32_e32 v45, 31, v44
	v_lshlrev_b64 v[14:15], 13, v[38:39]
	v_add_co_u32_e32 v0, vcc, s63, v0
	v_lshl_add_u64 v[6:7], v[4:5], 0, v[6:7]
	v_lshlrev_b64 v[8:9], 13, v[44:45]
	v_lshl_add_u64 v[14:15], v[4:5], 0, v[14:15]
	v_addc_co_u32_e32 v1, vcc, 0, v1, vcc
	v_lshl_add_u64 v[8:9], v[4:5], 0, v[8:9]
	global_load_dwordx2 v[76:77], v[6:7], off nt
	global_load_dwordx2 v[64:65], v[8:9], off nt
	global_load_dwordx2 v[52:53], v[14:15], off nt
	global_load_dwordx2 v[130:131], v[10:11], off offset:2048 nt
	global_load_dwordx2 v[68:69], v[12:13], off offset:-4096 nt
	global_load_dwordx2 v[132:133], v[12:13], off nt
	global_load_dwordx2 v[134:135], v[12:13], off offset:2048 nt
	global_load_dwordx2 v[136:137], v[0:1], off nt
	v_or_b32_e32 v14, 14, v96
	v_or_b32_e32 v12, 15, v3
	v_ashrrev_i32_e32 v15, 31, v14
	v_ashrrev_i32_e32 v13, 31, v12
	v_or_b32_e32 v24, 11, v96
	v_lshlrev_b64 v[10:11], 13, v[14:15]
	v_lshlrev_b64 v[16:17], 13, v[12:13]
	v_or_b32_e32 v22, 13, v96
	v_ashrrev_i32_e32 v25, 31, v24
	v_or_b32_e32 v20, 12, v96
	v_lshl_add_u64 v[10:11], v[4:5], 0, v[10:11]
	v_lshl_add_u64 v[16:17], v[4:5], 0, v[16:17]
	v_ashrrev_i32_e32 v23, 31, v22
	v_lshlrev_b64 v[6:7], 13, v[24:25]
	v_ashrrev_i32_e32 v21, 31, v20
	global_load_dwordx2 v[18:19], v[10:11], off nt
	s_nop 0
	global_load_dwordx2 v[16:17], v[16:17], off nt
	s_nop 0
	global_load_dwordx2 v[138:139], v[0:1], off offset:2048 nt
	v_lshlrev_b64 v[0:1], 13, v[22:23]
	v_lshl_add_u64 v[6:7], v[4:5], 0, v[6:7]
	v_lshlrev_b64 v[8:9], 13, v[20:21]
	v_lshl_add_u64 v[0:1], v[4:5], 0, v[0:1]
	v_lshl_add_u64 v[8:9], v[4:5], 0, v[8:9]
	global_load_dwordx2 v[60:61], v[6:7], off nt
	global_load_dwordx2 v[48:49], v[8:9], off nt
	global_load_dwordx2 v[28:29], v[0:1], off nt
	v_lshlrev_b32_e32 v0, 2, v2
	global_load_dwordx4 v[8:11], v0, s[4:5]
	global_load_dwordx4 v[4:7], v0, s[2:3]
	s_nop 0
	global_load_dwordx4 v[0:3], v0, s[22:23]
	s_waitcnt vmcnt(35)
	v_lshlrev_b32_e32 v144, 16, v30
	v_and_b32_e32 v145, 0xffff0000, v30
	v_lshlrev_b32_e32 v140, 16, v26
	v_and_b32_e32 v141, 0xffff0000, v26
	v_lshlrev_b32_e32 v146, 16, v31
	v_and_b32_e32 v147, 0xffff0000, v31
	s_waitcnt vmcnt(34)
	v_lshlrev_b32_e32 v148, 16, v32
	v_and_b32_e32 v149, 0xffff0000, v32
	v_lshlrev_b32_e32 v150, 16, v33
	v_and_b32_e32 v151, 0xffff0000, v33
	v_lshlrev_b32_e32 v142, 16, v27
	v_and_b32_e32 v143, 0xffff0000, v27
	v_lshl_add_u64 v[26:27], s[38:39], 0, v[168:169]
	v_lshlrev_b64 v[96:97], 12, v[96:97]
	v_lshl_add_u64 v[96:97], v[26:27], 0, v[96:97]
	s_waitcnt vmcnt(31)
	v_lshlrev_b32_e32 v152, 16, v34
	v_and_b32_e32 v153, 0xffff0000, v34
	v_lshlrev_b32_e32 v154, 16, v35
	v_and_b32_e32 v155, 0xffff0000, v35
	v_lshlrev_b64 v[104:105], 12, v[104:105]
	s_waitcnt vmcnt(24)
	v_lshlrev_b32_e32 v116, 16, v46
	v_and_b32_e32 v117, 0xffff0000, v46
	v_lshlrev_b32_e32 v118, 16, v47
	v_and_b32_e32 v119, 0xffff0000, v47
	s_waitcnt vmcnt(23)
; __device__ __forceinline__ unsigned cvt_pk_bf16(float lo, float hi) { unsigned r; asm volatile("v_cvt_pk_bf16_f32 %0, %1, %2" : "=v"(r) : "v"(lo), "v"(hi)); return r; }
; __device__ __forceinline__ float bf_lo(unsigned w) { return __uint_as_float(w << 16); }
; __device__ __forceinline__ float bf_hi(unsigned w) { return __uint_as_float(w & 0xffff0000u); }
; __global__ void __launch_bounds__(NTHR, 2) fwd_kernel(Args a) {
;     ...
;                 for (int i = 0; i < 18; ++i) u[i] = (f32x4){bf_lo(ub[i].x), bf_hi(ub[i].x), bf_lo(ub[i].y), bf_hi(ub[i].y)};
; #pragma unroll
;                 for (int i = 0; i < 16; ++i) { const f32x4 bgf = {bf_lo(bg[i].x), bf_hi(bg[i].x), bf_lo(bg[i].y), bf_hi(bg[i].y)};
;                     const f32x4 cu = (u[i] * w0 + u[i + 1] * w1 + u[i + 2] * w2v) * bgf;
;                     u32x2 w; w.x = cvt_pk_bf16(cu.x, cu.y); w.y = cvt_pk_bf16(cu.z, cu.w);
;                     *(u32x2*)(Y + (size_t)(row0 + i) * DM + c4) = w; }
	v_lshlrev_b32_e32 v108, 16, v50
	v_and_b32_e32 v109, 0xffff0000, v50
	v_lshlrev_b32_e32 v110, 16, v51
	v_and_b32_e32 v111, 0xffff0000, v51
	s_waitcnt vmcnt(19)
	v_lshlrev_b32_e32 v98, 16, v56
	v_and_b32_e32 v99, 0xffff0000, v56
	v_lshlrev_b32_e32 v102, 16, v57
	v_and_b32_e32 v103, 0xffff0000, v57
	s_waitcnt vmcnt(18)
	v_lshlrev_b32_e32 v86, 16, v58
	v_and_b32_e32 v87, 0xffff0000, v58
	v_lshlrev_b32_e32 v88, 16, v59
	v_and_b32_e32 v89, 0xffff0000, v59
	v_lshl_add_u64 v[104:105], v[26:27], 0, v[104:105]
	v_lshlrev_b32_e32 v156, 16, v40
	v_and_b32_e32 v157, 0xffff0000, v40
	v_lshlrev_b32_e32 v158, 16, v41
	v_and_b32_e32 v159, 0xffff0000, v41
	v_lshlrev_b64 v[100:101], 12, v[100:101]
	v_lshl_add_u64 v[100:101], v[26:27], 0, v[100:101]
	v_lshlrev_b32_e32 v160, 16, v36
	v_and_b32_e32 v161, 0xffff0000, v36
	v_lshlrev_b32_e32 v162, 16, v37
	v_and_b32_e32 v163, 0xffff0000, v37
	v_lshlrev_b64 v[90:91], 12, v[90:91]
	v_lshl_add_u64 v[90:91], v[26:27], 0, v[90:91]
	v_lshlrev_b32_e32 v120, 16, v42
	v_and_b32_e32 v121, 0xffff0000, v42
	v_lshlrev_b32_e32 v122, 16, v43
	s_waitcnt vmcnt(13)
	v_lshlrev_b32_e32 v56, 16, v130
	s_waitcnt vmcnt(11)
	v_lshlrev_b32_e32 v46, 16, v132
	s_waitcnt vmcnt(10)
	v_lshlrev_b32_e32 v30, 16, v134
	v_and_b32_e32 v31, 0xffff0000, v134
	v_lshlrev_b32_e32 v32, 16, v135
	v_and_b32_e32 v33, 0xffff0000, v135
	v_and_b32_e32 v47, 0xffff0000, v132
	v_lshlrev_b32_e32 v50, 16, v133
	v_and_b32_e32 v51, 0xffff0000, v133
	v_and_b32_e32 v57, 0xffff0000, v130
	v_lshlrev_b32_e32 v58, 16, v131
	v_and_b32_e32 v59, 0xffff0000, v131
	v_lshlrev_b32_e32 v130, 16, v128
	v_and_b32_e32 v131, 0xffff0000, v128
	v_lshlrev_b32_e32 v128, 16, v129
	v_and_b32_e32 v129, 0xffff0000, v129
	v_and_b32_e32 v123, 0xffff0000, v43
	v_lshlrev_b64 v[82:83], 12, v[82:83]
	v_lshl_add_u64 v[82:83], v[26:27], 0, v[82:83]
	v_lshlrev_b64 v[74:75], 12, v[74:75]
	v_lshl_add_u64 v[74:75], v[26:27], 0, v[74:75]
	v_lshlrev_b64 v[70:71], 12, v[70:71]
	v_lshl_add_u64 v[70:71], v[26:27], 0, v[70:71]
	v_lshlrev_b64 v[62:63], 12, v[62:63]
	v_lshl_add_u64 v[62:63], v[26:27], 0, v[62:63]
	s_waitcnt vmcnt(2)
	v_pk_mul_f32 v[134:135], v[8:9], v[144:145]
	v_pk_mul_f32 v[132:133], v[10:11], v[146:147]
	s_waitcnt vmcnt(1)
	v_pk_fma_f32 v[134:135], v[4:5], v[140:141], v[134:135]
	v_pk_fma_f32 v[132:133], v[6:7], v[142:143], v[132:133]
	s_waitcnt vmcnt(0)
	v_pk_fma_f32 v[134:135], v[0:1], v[148:149], v[134:135]
	v_pk_fma_f32 v[132:133], v[2:3], v[150:151], v[132:133]
	v_pk_mul_f32 v[130:131], v[134:135], v[130:131]
	v_pk_mul_f32 v[128:129], v[132:133], v[128:129]
	v_cvt_pk_bf16_f32 v130, v130, v131
	v_lshlrev_b64 v[54:55], 12, v[54:55]
	v_cvt_pk_bf16_f32 v131, v128, v129
	global_store_dwordx2 v[96:97], v[130:131], off
	v_pk_mul_f32 v[130:131], v[8:9], v[148:149]
	v_pk_mul_f32 v[128:129], v[10:11], v[150:151]
	v_pk_fma_f32 v[130:131], v[4:5], v[144:145], v[130:131]
	v_lshlrev_b32_e32 v96, 16, v112
	v_and_b32_e32 v97, 0xffff0000, v112
	v_pk_fma_f32 v[128:129], v[6:7], v[146:147], v[128:129]
	v_pk_fma_f32 v[130:131], v[0:1], v[152:153], v[130:131]
	v_lshlrev_b32_e32 v112, 16, v113
	v_and_b32_e32 v113, 0xffff0000, v113
	v_pk_fma_f32 v[128:129], v[2:3], v[154:155], v[128:129]
	v_pk_mul_f32 v[96:97], v[130:131], v[96:97]
	v_pk_mul_f32 v[112:113], v[128:129], v[112:113]
	v_cvt_pk_bf16_f32 v96, v96, v97
	v_lshl_add_u64 v[54:55], v[26:27], 0, v[54:55]
	v_cvt_pk_bf16_f32 v97, v112, v113
	global_store_dwordx2 v[104:105], v[96:97], off
	v_lshlrev_b32_e32 v96, 16, v114
	v_and_b32_e32 v97, 0xffff0000, v114
	v_lshlrev_b32_e32 v104, 16, v115
	v_and_b32_e32 v105, 0xffff0000, v115
	v_pk_mul_f32 v[112:113], v[10:11], v[154:155]
	v_pk_mul_f32 v[114:115], v[8:9], v[152:153]
	v_pk_fma_f32 v[112:113], v[6:7], v[150:151], v[112:113]
	v_pk_fma_f32 v[114:115], v[4:5], v[148:149], v[114:115]
	v_pk_fma_f32 v[112:113], v[2:3], v[158:159], v[112:113]
	v_pk_fma_f32 v[114:115], v[0:1], v[156:157], v[114:115]
	v_pk_mul_f32 v[104:105], v[112:113], v[104:105]
	v_pk_mul_f32 v[96:97], v[114:115], v[96:97]
	v_lshlrev_b32_e32 v78, 16, v66
	v_cvt_pk_bf16_f32 v96, v96, v97
	v_cvt_pk_bf16_f32 v97, v104, v105
	v_pk_mul_f32 v[104:105], v[8:9], v[156:157]
	global_store_dwordx2 v[100:101], v[96:97], off
	v_lshlrev_b32_e32 v96, 16, v106
	v_and_b32_e32 v97, 0xffff0000, v106
	v_lshlrev_b32_e32 v100, 16, v107
	v_and_b32_e32 v101, 0xffff0000, v107
	v_pk_mul_f32 v[106:107], v[10:11], v[158:159]
	v_pk_fma_f32 v[104:105], v[4:5], v[152:153], v[104:105]
	v_pk_fma_f32 v[106:107], v[6:7], v[154:155], v[106:107]
	v_pk_fma_f32 v[104:105], v[0:1], v[160:161], v[104:105]
	v_pk_fma_f32 v[106:107], v[2:3], v[162:163], v[106:107]
	v_pk_mul_f32 v[96:97], v[104:105], v[96:97]
	v_pk_mul_f32 v[100:101], v[106:107], v[100:101]
	v_cvt_pk_bf16_f32 v96, v96, v97
	v_and_b32_e32 v79, 0xffff0000, v66
	v_cvt_pk_bf16_f32 v97, v100, v101
	global_store_dwordx2 v[90:91], v[96:97], off
	v_pk_mul_f32 v[96:97], v[8:9], v[160:161]
	v_pk_mul_f32 v[100:101], v[10:11], v[162:163]
	v_pk_fma_f32 v[96:97], v[4:5], v[156:157], v[96:97]
	v_pk_fma_f32 v[100:101], v[6:7], v[158:159], v[100:101]
	v_lshlrev_b32_e32 v90, 16, v92
	v_and_b32_e32 v91, 0xffff0000, v92
	v_lshlrev_b32_e32 v92, 16, v93
	v_and_b32_e32 v93, 0xffff0000, v93
	v_pk_fma_f32 v[96:97], v[0:1], v[120:121], v[96:97]
	v_pk_fma_f32 v[100:101], v[2:3], v[122:123], v[100:101]
	v_pk_mul_f32 v[90:91], v[96:97], v[90:91]
	v_pk_mul_f32 v[92:93], v[100:101], v[92:93]
	v_cvt_pk_bf16_f32 v90, v90, v91
	v_lshlrev_b32_e32 v80, 16, v67
	v_cvt_pk_bf16_f32 v91, v92, v93
	v_pk_mul_f32 v[92:93], v[8:9], v[120:121]
	global_store_dwordx2 v[82:83], v[90:91], off
	v_lshlrev_b32_e32 v82, 16, v94
	v_and_b32_e32 v83, 0xffff0000, v94
; __device__ __forceinline__ unsigned cvt_pk_bf16(float lo, float hi) { unsigned r; asm volatile("v_cvt_pk_bf16_f32 %0, %1, %2" : "=v"(r) : "v"(lo), "v"(hi)); return r; }
; __device__ __forceinline__ float bf_lo(unsigned w) { return __uint_as_float(w << 16); }
; __device__ __forceinline__ float bf_hi(unsigned w) { return __uint_as_float(w & 0xffff0000u); }
; __global__ void __launch_bounds__(NTHR, 2) fwd_kernel(Args a) {
;     ...
; #pragma unroll
;                 for (int i = 0; i < 16; ++i) { const f32x4 bgf = {bf_lo(bg[i].x), bf_hi(bg[i].x), bf_lo(bg[i].y), bf_hi(bg[i].y)};
;                     const f32x4 cu = (u[i] * w0 + u[i + 1] * w1 + u[i + 2] * w2v) * bgf;
;                     u32x2 w; w.x = cvt_pk_bf16(cu.x, cu.y); w.y = cvt_pk_bf16(cu.z, cu.w);
;                     *(u32x2*)(Y + (size_t)(row0 + i) * DM + c4) = w; }
	v_lshlrev_b32_e32 v90, 16, v95
	v_and_b32_e32 v91, 0xffff0000, v95
	v_pk_mul_f32 v[94:95], v[10:11], v[122:123]
	v_pk_fma_f32 v[92:93], v[4:5], v[160:161], v[92:93]
	v_pk_fma_f32 v[94:95], v[6:7], v[162:163], v[94:95]
	v_pk_fma_f32 v[92:93], v[0:1], v[116:117], v[92:93]
	v_pk_fma_f32 v[94:95], v[2:3], v[118:119], v[94:95]
	v_pk_mul_f32 v[82:83], v[92:93], v[82:83]
	v_pk_mul_f32 v[90:91], v[94:95], v[90:91]
	v_cvt_pk_bf16_f32 v82, v82, v83
	v_and_b32_e32 v81, 0xffff0000, v67
	v_cvt_pk_bf16_f32 v83, v90, v91
	global_store_dwordx2 v[74:75], v[82:83], off
	v_lshlrev_b32_e32 v74, 16, v84
	v_and_b32_e32 v75, 0xffff0000, v84
	v_lshlrev_b32_e32 v82, 16, v85
	v_and_b32_e32 v83, 0xffff0000, v85
	v_pk_mul_f32 v[84:85], v[8:9], v[116:117]
	v_pk_mul_f32 v[90:91], v[10:11], v[118:119]
	v_pk_fma_f32 v[84:85], v[4:5], v[120:121], v[84:85]
	v_pk_fma_f32 v[90:91], v[6:7], v[122:123], v[90:91]
	v_pk_fma_f32 v[84:85], v[0:1], v[108:109], v[84:85]
	v_pk_fma_f32 v[90:91], v[2:3], v[110:111], v[90:91]
	v_pk_mul_f32 v[74:75], v[84:85], v[74:75]
	v_pk_mul_f32 v[82:83], v[90:91], v[82:83]
	v_cvt_pk_bf16_f32 v74, v74, v75
	v_lshlrev_b64 v[44:45], 12, v[44:45]
	v_cvt_pk_bf16_f32 v75, v82, v83
	global_store_dwordx2 v[70:71], v[74:75], off
	v_pk_mul_f32 v[74:75], v[8:9], v[108:109]
	v_pk_mul_f32 v[82:83], v[10:11], v[110:111]
	v_pk_fma_f32 v[74:75], v[4:5], v[116:117], v[74:75]
	v_pk_fma_f32 v[82:83], v[6:7], v[118:119], v[82:83]
	v_lshlrev_b32_e32 v70, 16, v72
	v_and_b32_e32 v71, 0xffff0000, v72
	v_lshlrev_b32_e32 v72, 16, v73
	v_and_b32_e32 v73, 0xffff0000, v73
	v_pk_fma_f32 v[74:75], v[0:1], v[98:99], v[74:75]
	v_pk_fma_f32 v[82:83], v[2:3], v[102:103], v[82:83]
	v_pk_mul_f32 v[70:71], v[74:75], v[70:71]
	v_pk_mul_f32 v[72:73], v[82:83], v[72:73]
	v_cvt_pk_bf16_f32 v70, v70, v71
	v_pk_mul_f32 v[74:75], v[10:11], v[102:103]
	v_cvt_pk_bf16_f32 v71, v72, v73
	v_pk_mul_f32 v[72:73], v[8:9], v[98:99]
	global_store_dwordx2 v[62:63], v[70:71], off
	v_pk_fma_f32 v[72:73], v[4:5], v[108:109], v[72:73]
	v_lshlrev_b32_e32 v62, 16, v76
	v_and_b32_e32 v63, 0xffff0000, v76
	v_pk_fma_f32 v[74:75], v[6:7], v[110:111], v[74:75]
	v_pk_fma_f32 v[72:73], v[0:1], v[86:87], v[72:73]
	v_lshlrev_b32_e32 v70, 16, v77
	v_and_b32_e32 v71, 0xffff0000, v77
	v_pk_fma_f32 v[74:75], v[2:3], v[88:89], v[74:75]
	v_pk_mul_f32 v[62:63], v[72:73], v[62:63]
	v_pk_mul_f32 v[70:71], v[74:75], v[70:71]
	v_cvt_pk_bf16_f32 v62, v62, v63
	v_lshl_add_u64 v[44:45], v[26:27], 0, v[44:45]
	v_cvt_pk_bf16_f32 v63, v70, v71
	global_store_dwordx2 v[54:55], v[62:63], off
	v_lshlrev_b32_e32 v54, 16, v64
	v_and_b32_e32 v55, 0xffff0000, v64
	v_lshlrev_b32_e32 v62, 16, v65
	v_and_b32_e32 v63, 0xffff0000, v65
	v_pk_mul_f32 v[64:65], v[8:9], v[86:87]
	v_pk_mul_f32 v[70:71], v[10:11], v[88:89]
	v_pk_fma_f32 v[64:65], v[4:5], v[98:99], v[64:65]
	v_pk_fma_f32 v[70:71], v[6:7], v[102:103], v[70:71]
	v_pk_fma_f32 v[64:65], v[0:1], v[78:79], v[64:65]
	v_pk_fma_f32 v[70:71], v[2:3], v[80:81], v[70:71]
	v_pk_mul_f32 v[54:55], v[64:65], v[54:55]
	v_pk_mul_f32 v[62:63], v[70:71], v[62:63]
	v_cvt_pk_bf16_f32 v54, v54, v55
	v_lshlrev_b32_e32 v66, 16, v68
	v_cvt_pk_bf16_f32 v55, v62, v63
	global_store_dwordx2 v[44:45], v[54:55], off
	v_pk_mul_f32 v[54:55], v[8:9], v[78:79]
	v_pk_mul_f32 v[62:63], v[10:11], v[80:81]
	v_and_b32_e32 v67, 0xffff0000, v68
	v_lshlrev_b32_e32 v68, 16, v69
	v_and_b32_e32 v69, 0xffff0000, v69
	v_pk_fma_f32 v[62:63], v[6:7], v[88:89], v[62:63]
	v_pk_fma_f32 v[54:55], v[4:5], v[86:87], v[54:55]
	v_lshlrev_b32_e32 v44, 16, v52
	v_and_b32_e32 v45, 0xffff0000, v52
	v_lshlrev_b32_e32 v52, 16, v53
	v_and_b32_e32 v53, 0xffff0000, v53
	v_pk_fma_f32 v[54:55], v[0:1], v[66:67], v[54:55]
	v_pk_fma_f32 v[62:63], v[2:3], v[68:69], v[62:63]
	v_pk_mul_f32 v[44:45], v[54:55], v[44:45]
	v_pk_mul_f32 v[52:53], v[62:63], v[52:53]
	v_cvt_pk_bf16_f32 v44, v44, v45
	v_lshlrev_b64 v[38:39], 12, v[38:39]
	v_cvt_pk_bf16_f32 v45, v52, v53
	v_pk_mul_f32 v[52:53], v[8:9], v[66:67]
	v_pk_mul_f32 v[54:55], v[10:11], v[68:69]
	v_lshl_add_u64 v[38:39], v[26:27], 0, v[38:39]
	v_pk_fma_f32 v[54:55], v[6:7], v[80:81], v[54:55]
	v_pk_fma_f32 v[52:53], v[4:5], v[78:79], v[52:53]
	global_store_dwordx2 v[38:39], v[44:45], off
	v_lshlrev_b32_e32 v38, 16, v60
	v_and_b32_e32 v39, 0xffff0000, v60
	v_lshlrev_b32_e32 v44, 16, v61
	v_and_b32_e32 v45, 0xffff0000, v61
; __device__ __forceinline__ unsigned cvt_pk_bf16(float lo, float hi) { unsigned r; asm volatile("v_cvt_pk_bf16_f32 %0, %1, %2" : "=v"(r) : "v"(lo), "v"(hi)); return r; }
; __device__ __forceinline__ float bf_lo(unsigned w) { return __uint_as_float(w << 16); }
; __device__ __forceinline__ float bf_hi(unsigned w) { return __uint_as_float(w & 0xffff0000u); }
; __global__ void __launch_bounds__(NTHR, 2) fwd_kernel(Args a) {
;     ...
;             for (int rc_ = 0; rc_ < REP_M1C; ++rc_) for (int item = gt; item < (MP / 16) * 256; item += NGT) {
;                 const int c4 = (item & 255) * 4, row0 = (item >> 8) * 16; const bool cont = (row0 & (SEQ - 1)) != 0; const bf16_t* up = (const bf16_t*)UC + (size_t)row0 * CONVD + c4; const f32x4 z = {0.f, 0.f, 0.f, 0.f};
;                 f32x4 u[18]; u32x2 bg[16];
;                 u32x2 ub[18]; ub[0] = cont ? *(const u32x2*)(up - 2 * CONVD) : (u32x2){0u, 0u}; ub[1] = cont ? *(const u32x2*)(up - CONVD) : (u32x2){0u, 0u};
;     ...
; #pragma unroll
;                 for (int i = 0; i < 16; ++i) { const f32x4 bgf = {bf_lo(bg[i].x), bf_hi(bg[i].x), bf_lo(bg[i].y), bf_hi(bg[i].y)};
;                     const f32x4 cu = (u[i] * w0 + u[i + 1] * w1 + u[i + 2] * w2v) * bgf;
;                     u32x2 w; w.x = cvt_pk_bf16(cu.x, cu.y); w.y = cvt_pk_bf16(cu.z, cu.w);
;                     *(u32x2*)(Y + (size_t)(row0 + i) * DM + c4) = w; }
;             }
	v_pk_fma_f32 v[52:53], v[0:1], v[56:57], v[52:53]
	v_pk_fma_f32 v[54:55], v[2:3], v[58:59], v[54:55]
	v_pk_mul_f32 v[38:39], v[52:53], v[38:39]
	v_pk_mul_f32 v[44:45], v[54:55], v[44:45]
	v_lshlrev_b64 v[24:25], 12, v[24:25]
	v_cvt_pk_bf16_f32 v38, v38, v39
	v_cvt_pk_bf16_f32 v39, v44, v45
	v_lshl_add_u64 v[24:25], v[26:27], 0, v[24:25]
	v_pk_mul_f32 v[44:45], v[8:9], v[56:57]
	global_store_dwordx2 v[24:25], v[38:39], off
	v_lshlrev_b32_e32 v24, 16, v48
	v_and_b32_e32 v25, 0xffff0000, v48
	v_lshlrev_b32_e32 v38, 16, v49
	v_and_b32_e32 v39, 0xffff0000, v49
	v_pk_mul_f32 v[48:49], v[10:11], v[58:59]
	v_pk_fma_f32 v[44:45], v[4:5], v[66:67], v[44:45]
	v_pk_fma_f32 v[48:49], v[6:7], v[68:69], v[48:49]
	v_pk_fma_f32 v[44:45], v[0:1], v[46:47], v[44:45]
	v_pk_fma_f32 v[48:49], v[2:3], v[50:51], v[48:49]
	v_pk_mul_f32 v[24:25], v[44:45], v[24:25]
	v_lshlrev_b64 v[20:21], 12, v[20:21]
	v_pk_mul_f32 v[38:39], v[48:49], v[38:39]
	v_cvt_pk_bf16_f32 v24, v24, v25
	v_lshl_add_u64 v[20:21], v[26:27], 0, v[20:21]
	v_cvt_pk_bf16_f32 v25, v38, v39
	global_store_dwordx2 v[20:21], v[24:25], off
	v_lshlrev_b32_e32 v20, 16, v28
	v_and_b32_e32 v21, 0xffff0000, v28
	v_lshlrev_b32_e32 v24, 16, v29
	v_and_b32_e32 v25, 0xffff0000, v29
	v_pk_mul_f32 v[28:29], v[8:9], v[46:47]
	v_pk_mul_f32 v[38:39], v[10:11], v[50:51]
	v_pk_fma_f32 v[28:29], v[4:5], v[56:57], v[28:29]
	v_pk_fma_f32 v[38:39], v[6:7], v[58:59], v[38:39]
	v_pk_fma_f32 v[28:29], v[0:1], v[30:31], v[28:29]
	v_lshlrev_b64 v[22:23], 12, v[22:23]
	v_pk_fma_f32 v[38:39], v[2:3], v[32:33], v[38:39]
	v_pk_mul_f32 v[20:21], v[28:29], v[20:21]
	v_lshl_add_u64 v[22:23], v[26:27], 0, v[22:23]
	v_pk_mul_f32 v[24:25], v[38:39], v[24:25]
	v_cvt_pk_bf16_f32 v20, v20, v21
	v_lshlrev_b32_e32 v40, 16, v136
	v_cvt_pk_bf16_f32 v21, v24, v25
	global_store_dwordx2 v[22:23], v[20:21], off
	v_pk_mul_f32 v[22:23], v[8:9], v[30:31]
	v_and_b32_e32 v41, 0xffff0000, v136
	v_lshlrev_b32_e32 v42, 16, v137
	v_and_b32_e32 v43, 0xffff0000, v137
	v_pk_mul_f32 v[24:25], v[10:11], v[32:33]
	v_pk_fma_f32 v[22:23], v[4:5], v[46:47], v[22:23]
	v_lshlrev_b32_e32 v20, 16, v18
	v_and_b32_e32 v21, 0xffff0000, v18
	v_pk_fma_f32 v[24:25], v[6:7], v[50:51], v[24:25]
	v_pk_fma_f32 v[22:23], v[0:1], v[40:41], v[22:23]
	v_lshlrev_b64 v[14:15], 12, v[14:15]
	v_pk_mul_f32 v[8:9], v[8:9], v[40:41]
	v_pk_mul_f32 v[10:11], v[10:11], v[42:43]
	v_lshlrev_b32_e32 v36, 16, v138
	v_and_b32_e32 v37, 0xffff0000, v138
	v_lshlrev_b32_e32 v34, 16, v139
	v_and_b32_e32 v35, 0xffff0000, v139
	v_lshlrev_b32_e32 v18, 16, v19
	v_and_b32_e32 v19, 0xffff0000, v19
	v_pk_fma_f32 v[24:25], v[2:3], v[42:43], v[24:25]
	v_pk_mul_f32 v[20:21], v[22:23], v[20:21]
	v_lshl_add_u64 v[14:15], v[26:27], 0, v[14:15]
	v_pk_fma_f32 v[6:7], v[6:7], v[32:33], v[10:11]
	v_pk_fma_f32 v[4:5], v[4:5], v[30:31], v[8:9]
	v_pk_mul_f32 v[18:19], v[24:25], v[18:19]
	v_cvt_pk_bf16_f32 v20, v20, v21
	v_pk_fma_f32 v[0:1], v[0:1], v[36:37], v[4:5]
	v_cvt_pk_bf16_f32 v21, v18, v19
	global_store_dwordx2 v[14:15], v[20:21], off
	v_lshlrev_b32_e32 v14, 16, v16
	v_and_b32_e32 v15, 0xffff0000, v16
	v_lshlrev_b32_e32 v16, 16, v17
	v_and_b32_e32 v17, 0xffff0000, v17
	v_pk_fma_f32 v[2:3], v[2:3], v[34:35], v[6:7]
	v_pk_mul_f32 v[0:1], v[0:1], v[14:15]
	v_pk_mul_f32 v[2:3], v[2:3], v[16:17]
	v_add_u32_e32 v127, s76, v127
	s_mov_b32 s6, 0x1ffff
	v_cvt_pk_bf16_f32 v0, v0, v1
	v_cvt_pk_bf16_f32 v1, v2, v3
	v_lshlrev_b64 v[2:3], 12, v[12:13]
	v_cmp_lt_i32_e32 vcc, s6, v127
	v_lshl_add_u64 v[2:3], v[26:27], 0, v[2:3]
	s_or_b64 s[40:41], vcc, s[40:41]
	v_add_u32_e32 v126, s58, v126
	global_store_dwordx2 v[2:3], v[0:1], off
	s_andn2_b64 exec, exec, s[40:41]
	s_cbranch_execz .LBB0_373
.LBB0_371:
	v_ashrrev_i32_e32 v3, 4, v127
	v_and_b32_e32 v96, -16, v3
	v_and_b32_e32 v0, 0x7f00, v127
	v_ashrrev_i32_e32 v97, 31, v96
	v_and_b32_e32 v2, 0x3fc, v126
	v_cmp_ne_u32_e32 vcc, 0, v0
	v_lshlrev_b64 v[0:1], 11, v[96:97]
	v_lshl_add_u64 v[0:1], s[28:29], 0, v[0:1]
	v_lshlrev_b32_e32 v168, 1, v2
	v_mov_b32_e32 v26, 0
	v_lshl_add_u64 v[0:1], v[0:1], 0, v[168:169]
	v_mov_b32_e32 v27, 0
	v_mov_b32_e32 v30, 0
	v_mov_b32_e32 v31, 0
	s_and_saveexec_b64 s[6:7], vcc
	s_cbranch_execz .LBB0_370
	global_load_dwordx2 v[26:27], v[0:1], off offset:-4096 nt
	global_load_dwordx2 v[30:31], v[0:1], off offset:-2048 nt
	s_branch .LBB0_370

; __device__ __forceinline__ unsigned cvt_pk_bf16(float lo, float hi) { unsigned r; asm volatile("v_cvt_pk_bf16_f32 %0, %1, %2" : "=v"(r) : "v"(lo), "v"(hi)); return r; }
; __device__ __forceinline__ float bf_lo(unsigned w) { return __uint_as_float(w << 16); }
; __device__ __forceinline__ float bf_hi(unsigned w) { return __uint_as_float(w & 0xffff0000u); }
; __global__ void __launch_bounds__(NTHR, 2) fwd_kernel(Args a) {
;     ...
;         for (int e = gt; e < 16 * DK * 64; e += NGT) { const int bh = e >> 13, rem = e & 8191, k = rem >> 6, dq = rem & 63;
;             bf16_t* sp = SUB + (size_t)bh * NCH * (DK * DV) + k * DV + 4 * dq; const float* ep = EB + (size_t)bh * NCH * DK + k; f32x4 S = {0.f, 0.f, 0.f, 0.f};
; #pragma unroll 1
;             for (int c0 = 0; c0 < NCH; c0 += 16) { u32x2 uu[16]; float ee[16];
; #pragma unroll
;                 for (int i = 0; i < 16; ++i) { uu[i] = *(const u32x2*)(sp + (size_t)(c0 + i) * (DK * DV)); ee[i] = ep[(c0 + i) * DK]; }
; #pragma unroll
;                 for (int i = 0; i < 16; ++i) { u32x2 w; w.x = cvt_pk_bf16(S.x, S.y); w.y = cvt_pk_bf16(S.z, S.w); *(u32x2*)(sp + (size_t)(c0 + i) * (DK * DV)) = w;
;                     S = S * ee[i] + (f32x4){bf_lo(uu[i].x), bf_hi(uu[i].x), bf_lo(uu[i].y), bf_hi(uu[i].y)}; } }
.LBB0_431:
	s_or_b32 s9, s7, 1
	s_lshl_b32 s6, s9, 16
	s_lshl_b32 s82, s9, 7
	s_or_b32 s9, s7, 2
	s_lshl_b32 s80, s9, 16
	s_lshl_b32 s78, s9, 7
	s_or_b32 s9, s7, 3
	s_lshl_b32 s68, s9, 16
	s_lshl_b32 s96, s9, 7
	s_or_b32 s9, s7, 4
	s_lshl_b32 s94, s9, 16
	s_lshl_b32 s92, s9, 7
	s_or_b32 s9, s7, 5
	s_lshl_b32 s90, s9, 16
	s_lshl_b32 s88, s9, 7
	s_or_b32 s9, s7, 6
	s_lshl_b32 s72, s9, 16
	s_lshl_b32 s74, s9, 7
	s_or_b32 s9, s7, 7
	s_lshl_b32 s30, s9, 16
	s_lshl_b32 s86, s9, 7
	s_or_b32 s9, s7, 8
	s_lshl_b32 s66, s9, 16
	s_lshl_b32 s64, s9, 7
	s_or_b32 s9, s7, 9
	s_lshl_b32 s62, s9, 16
	s_lshl_b32 s60, s9, 7
	s_or_b32 s9, s7, 10
	s_lshl_b32 s58, s9, 16
	s_lshl_b32 s56, s9, 7
	s_or_b32 s9, s7, 11
	s_lshl_b32 s54, s9, 16
	s_lshl_b32 s52, s9, 7
	s_or_b32 s9, s7, 12
	s_lshl_b32 s50, s9, 16
	s_lshl_b32 s48, s9, 7
	s_or_b32 s9, s7, 13
	s_lshl_b32 s10, s7, 16
	s_lshl_b32 s46, s9, 16
	s_lshl_b32 s44, s9, 7
	s_or_b32 s9, s7, 14
	s_lshl_b32 s8, s7, 7
	s_lshl_b32 s42, s9, 16
	s_lshl_b32 s40, s9, 7
	v_lshl_add_u64 v[14:15], v[10:11], 0, s[10:11]
	s_mov_b32 s9, s11
	s_or_b32 s7, s7, 15
	global_load_dwordx2 v[16:17], v[14:15], off nt
	v_lshl_add_u64 v[18:19], s[8:9], 2, v[12:13]
	s_mov_b32 s83, s11
	s_mov_b32 s97, s11
	s_mov_b32 s89, s11
	s_mov_b32 s87, s11
	s_mov_b32 s61, s11
	s_mov_b32 s57, s11
	v_cndmask_b32_e64 v9, 0, 1, s[34:35]
	s_lshl_b32 s38, s7, 16
	s_lshl_b32 s34, s7, 7
	global_load_dword v40, v[18:19], off nt
	s_mov_b32 s7, s11
	v_lshl_add_u64 v[20:21], s[82:83], 2, v[12:13]
	v_lshl_add_u64 v[22:23], s[96:97], 2, v[12:13]
	v_lshl_add_u64 v[26:27], s[88:89], 2, v[12:13]
	v_lshl_add_u64 v[30:31], s[86:87], 2, v[12:13]
	v_lshl_add_u64 v[34:35], s[60:61], 2, v[12:13]
	v_lshl_add_u64 v[38:39], s[56:57], 2, v[12:13]
	global_load_dword v36, v[20:21], off nt
	global_load_dword v48, v[22:23], off nt
	global_load_dword v54, v[26:27], off nt
	global_load_dword v58, v[30:31], off nt
	global_load_dword v62, v[34:35], off nt
	global_load_dword v64, v[38:39], off nt
	v_lshl_add_u64 v[18:19], v[10:11], 0, s[6:7]
	global_load_dwordx2 v[18:19], v[18:19], off nt
	s_mov_b32 s81, s11
	s_mov_b32 s95, s11
	s_mov_b32 s73, s11
	v_lshl_add_u64 v[20:21], v[10:11], 0, s[80:81]
	s_mov_b32 s79, s11
	v_lshl_add_u64 v[22:23], v[10:11], 0, s[94:95]
	v_lshl_add_u64 v[26:27], v[10:11], 0, s[72:73]
	global_load_dwordx2 v[44:45], v[20:21], off nt
	s_mov_b32 s93, s11
	global_load_dwordx2 v[22:23], v[22:23], off nt
	s_mov_b32 s75, s11
	global_load_dwordx2 v[26:27], v[26:27], off nt
	v_lshl_add_u64 v[20:21], s[78:79], 2, v[12:13]
	s_mov_b32 s67, s11
	global_load_dword v72, v[20:21], off nt
	s_mov_b32 s69, s11
	v_lshl_add_u64 v[24:25], s[92:93], 2, v[12:13]
	v_lshl_add_u64 v[28:29], s[74:75], 2, v[12:13]
	v_lshl_add_u64 v[30:31], v[10:11], 0, s[66:67]
	global_load_dword v52, v[24:25], off nt
	global_load_dword v56, v[28:29], off nt
	s_mov_b32 s91, s11
	global_load_dwordx2 v[30:31], v[30:31], off nt
	v_lshl_add_u64 v[20:21], v[10:11], 0, s[68:69]
	global_load_dwordx2 v[20:21], v[20:21], off nt
	v_lshl_add_u64 v[24:25], v[10:11], 0, s[90:91]
	global_load_dwordx2 v[24:25], v[24:25], off nt
	s_mov_b32 s31, s11
	v_lshl_add_u64 v[28:29], v[10:11], 0, s[30:31]
	global_load_dwordx2 v[28:29], v[28:29], off nt
	s_mov_b32 s65, s11
	v_lshl_add_u64 v[32:33], s[64:65], 2, v[12:13]
	global_load_dword v60, v[32:33], off nt
	s_mov_b32 s63, s11
	v_lshl_add_u64 v[32:33], v[10:11], 0, s[62:63]
	global_load_dwordx2 v[32:33], v[32:33], off nt
	s_mov_b32 s59, s11
	v_lshl_add_u64 v[34:35], v[10:11], 0, s[58:59]
	global_load_dwordx2 v[34:35], v[34:35], off nt
	s_mov_b32 s55, s11
	v_lshl_add_u64 v[38:39], v[10:11], 0, s[54:55]
	s_mov_b32 s53, s11
	global_load_dwordx2 v[38:39], v[38:39], off nt
	v_lshl_add_u64 v[42:43], s[52:53], 2, v[12:13]
	global_load_dword v66, v[42:43], off nt
	s_mov_b32 s51, s11
	v_lshl_add_u64 v[42:43], v[10:11], 0, s[50:51]
	s_mov_b32 s49, s11
	global_load_dwordx2 v[42:43], v[42:43], off nt
	v_lshl_add_u64 v[46:47], s[48:49], 2, v[12:13]
	s_mov_b32 s45, s11
	s_mov_b32 s41, s11
	s_mov_b32 s35, s11
	global_load_dword v68, v[46:47], off nt
	s_mov_b32 s47, s11
	v_lshl_add_u64 v[50:51], s[44:45], 2, v[12:13]
	v_lshl_add_u64 v[70:71], s[40:41], 2, v[12:13]
	v_lshl_add_u64 v[78:79], s[34:35], 2, v[12:13]
	global_load_dword v74, v[50:51], off nt
	global_load_dword v76, v[70:71], off nt
	s_mov_b32 s43, s11
	global_load_dword v78, v[78:79], off nt
	v_lshl_add_u64 v[46:47], v[10:11], 0, s[46:47]
	global_load_dwordx2 v[46:47], v[46:47], off nt
	v_lshl_add_u64 v[50:51], v[10:11], 0, s[42:43]
	global_load_dwordx2 v[50:51], v[50:51], off nt
	s_mov_b32 s39, s11
	v_lshl_add_u64 v[70:71], v[10:11], 0, s[38:39]
	global_load_dwordx2 v[70:71], v[70:71], off nt
	v_cvt_pk_bf16_f32 v80, v0, v1
	v_cvt_pk_bf16_f32 v81, v2, v3
	global_store_dwordx2 v[14:15], v[80:81], off
	s_waitcnt vmcnt(32)
	v_lshlrev_b32_e32 v80, 16, v16
	v_and_b32_e32 v81, 0xffff0000, v16
	v_lshlrev_b32_e32 v16, 16, v17
	v_and_b32_e32 v17, 0xffff0000, v17
	s_mov_b32 s6, 0x10000
	s_waitcnt vmcnt(31)
	v_pk_fma_f32 v[2:3], v[2:3], v[40:41], v[16:17] op_sel_hi:[1,0,1]
	v_pk_fma_f32 v[0:1], v[0:1], v[40:41], v[80:81] op_sel_hi:[1,0,1]
	v_add_co_u32_e64 v40, s[40:41], s6, v14
	v_cvt_pk_bf16_f32 v16, v0, v1
	v_cvt_pk_bf16_f32 v17, v2, v3
	s_mov_b32 s6, 0x30000
	s_nop 0
	v_addc_co_u32_e64 v41, s[40:41], 0, v15, s[40:41]
	global_store_dwordx2 v[40:41], v[16:17], off
	s_waitcnt vmcnt(25)
	v_lshlrev_b32_e32 v16, 16, v18
	v_and_b32_e32 v17, 0xffff0000, v18
	v_lshlrev_b32_e32 v18, 16, v19
	v_and_b32_e32 v19, 0xffff0000, v19
	v_pk_fma_f32 v[2:3], v[2:3], v[36:37], v[18:19] op_sel_hi:[1,0,1]
	v_add_co_u32_e64 v18, s[40:41], s70, v14
	v_pk_fma_f32 v[0:1], v[0:1], v[36:37], v[16:17] op_sel_hi:[1,0,1]
	s_nop 0
	v_addc_co_u32_e64 v19, s[40:41], 0, v15, s[40:41]
	v_cvt_pk_bf16_f32 v16, v0, v1
	v_cvt_pk_bf16_f32 v17, v2, v3
	global_store_dwordx2 v[18:19], v[16:17], off
	s_waitcnt vmcnt(25)
; __device__ __forceinline__ unsigned cvt_pk_bf16(float lo, float hi) { unsigned r; asm volatile("v_cvt_pk_bf16_f32 %0, %1, %2" : "=v"(r) : "v"(lo), "v"(hi)); return r; }
; __device__ __forceinline__ float bf_lo(unsigned w) { return __uint_as_float(w << 16); }
; __device__ __forceinline__ float bf_hi(unsigned w) { return __uint_as_float(w & 0xffff0000u); }
; __global__ void __launch_bounds__(NTHR, 2) fwd_kernel(Args a) {
;     ...
; #pragma unroll
;                 for (int i = 0; i < 16; ++i) { u32x2 w; w.x = cvt_pk_bf16(S.x, S.y); w.y = cvt_pk_bf16(S.z, S.w); *(u32x2*)(sp + (size_t)(c0 + i) * (DK * DV)) = w;
;                     S = S * ee[i] + (f32x4){bf_lo(uu[i].x), bf_hi(uu[i].x), bf_lo(uu[i].y), bf_hi(uu[i].y)}; } }
	v_lshlrev_b32_e32 v18, 16, v45
	v_and_b32_e32 v19, 0xffff0000, v45
	s_waitcnt vmcnt(22)
	v_pk_fma_f32 v[2:3], v[2:3], v[72:73], v[18:19] op_sel_hi:[1,0,1]
	v_add_co_u32_e64 v18, s[40:41], s6, v14
	v_lshlrev_b32_e32 v16, 16, v44
	v_and_b32_e32 v17, 0xffff0000, v44
	v_addc_co_u32_e64 v19, s[40:41], 0, v15, s[40:41]
	v_pk_fma_f32 v[0:1], v[0:1], v[72:73], v[16:17] op_sel_hi:[1,0,1]
	s_mov_b32 s6, 0x40000
	v_cvt_pk_bf16_f32 v16, v0, v1
	v_cvt_pk_bf16_f32 v17, v2, v3
	global_store_dwordx2 v[18:19], v[16:17], off
	s_waitcnt vmcnt(19)
	v_lshlrev_b32_e32 v18, 16, v21
	v_and_b32_e32 v19, 0xffff0000, v21
	v_pk_fma_f32 v[2:3], v[2:3], v[48:49], v[18:19] op_sel_hi:[1,0,1]
	v_add_co_u32_e64 v18, s[40:41], s6, v14
	v_lshlrev_b32_e32 v16, 16, v20
	v_and_b32_e32 v17, 0xffff0000, v20
	v_addc_co_u32_e64 v19, s[40:41], 0, v15, s[40:41]
	v_pk_fma_f32 v[0:1], v[0:1], v[48:49], v[16:17] op_sel_hi:[1,0,1]
	s_mov_b32 s6, 0x50000
	v_cvt_pk_bf16_f32 v16, v0, v1
	v_cvt_pk_bf16_f32 v17, v2, v3
	global_store_dwordx2 v[18:19], v[16:17], off
	v_lshlrev_b32_e32 v18, 16, v23
	v_and_b32_e32 v19, 0xffff0000, v23
	v_pk_fma_f32 v[2:3], v[2:3], v[52:53], v[18:19] op_sel_hi:[1,0,1]
	v_add_co_u32_e64 v18, s[40:41], s6, v14
	v_lshlrev_b32_e32 v16, 16, v22
	v_and_b32_e32 v17, 0xffff0000, v22
	v_addc_co_u32_e64 v19, s[40:41], 0, v15, s[40:41]
	v_pk_fma_f32 v[0:1], v[0:1], v[52:53], v[16:17] op_sel_hi:[1,0,1]
	s_mov_b32 s6, 0x60000
	v_cvt_pk_bf16_f32 v16, v0, v1
	v_cvt_pk_bf16_f32 v17, v2, v3
	global_store_dwordx2 v[18:19], v[16:17], off
	s_waitcnt vmcnt(20)
	v_lshlrev_b32_e32 v18, 16, v25
	v_and_b32_e32 v19, 0xffff0000, v25
	v_pk_fma_f32 v[2:3], v[2:3], v[54:55], v[18:19] op_sel_hi:[1,0,1]
	v_add_co_u32_e64 v18, s[40:41], s6, v14
	v_lshlrev_b32_e32 v16, 16, v24
	v_and_b32_e32 v17, 0xffff0000, v24
	v_addc_co_u32_e64 v19, s[40:41], 0, v15, s[40:41]
	v_pk_fma_f32 v[0:1], v[0:1], v[54:55], v[16:17] op_sel_hi:[1,0,1]
	s_mov_b32 s6, 0x70000
	v_cvt_pk_bf16_f32 v16, v0, v1
	v_cvt_pk_bf16_f32 v17, v2, v3
	global_store_dwordx2 v[18:19], v[16:17], off
	v_lshlrev_b32_e32 v18, 16, v27
	v_and_b32_e32 v19, 0xffff0000, v27
	v_pk_fma_f32 v[2:3], v[2:3], v[56:57], v[18:19] op_sel_hi:[1,0,1]
	v_add_co_u32_e64 v18, s[40:41], s6, v14
	v_lshlrev_b32_e32 v16, 16, v26
	v_and_b32_e32 v17, 0xffff0000, v26
	v_addc_co_u32_e64 v19, s[40:41], 0, v15, s[40:41]
	v_pk_fma_f32 v[0:1], v[0:1], v[56:57], v[16:17] op_sel_hi:[1,0,1]
	s_mov_b32 s6, 0x80000
	v_cvt_pk_bf16_f32 v16, v0, v1
	v_cvt_pk_bf16_f32 v17, v2, v3
	global_store_dwordx2 v[18:19], v[16:17], off
	s_waitcnt vmcnt(21)
	v_lshlrev_b32_e32 v18, 16, v29
	v_and_b32_e32 v19, 0xffff0000, v29
	v_pk_fma_f32 v[2:3], v[2:3], v[58:59], v[18:19] op_sel_hi:[1,0,1]
	v_add_co_u32_e64 v18, s[40:41], s6, v14
	v_lshlrev_b32_e32 v16, 16, v28
	v_and_b32_e32 v17, 0xffff0000, v28
	v_addc_co_u32_e64 v19, s[40:41], 0, v15, s[40:41]
	v_pk_fma_f32 v[0:1], v[0:1], v[58:59], v[16:17] op_sel_hi:[1,0,1]
	s_mov_b32 s6, 0x90000
	v_cvt_pk_bf16_f32 v16, v0, v1
	v_cvt_pk_bf16_f32 v17, v2, v3
	global_store_dwordx2 v[18:19], v[16:17], off
	v_lshlrev_b32_e32 v18, 16, v31
	v_and_b32_e32 v19, 0xffff0000, v31
	s_waitcnt vmcnt(21)
	v_pk_fma_f32 v[2:3], v[2:3], v[60:61], v[18:19] op_sel_hi:[1,0,1]
	v_add_co_u32_e64 v18, s[40:41], s6, v14
	v_lshlrev_b32_e32 v16, 16, v30
	v_and_b32_e32 v17, 0xffff0000, v30
	v_addc_co_u32_e64 v19, s[40:41], 0, v15, s[40:41]
	v_pk_fma_f32 v[0:1], v[0:1], v[60:61], v[16:17] op_sel_hi:[1,0,1]
	s_mov_b32 s6, 0xa0000
	v_cvt_pk_bf16_f32 v16, v0, v1
	v_cvt_pk_bf16_f32 v17, v2, v3
	global_store_dwordx2 v[18:19], v[16:17], off
	s_waitcnt vmcnt(21)
	v_lshlrev_b32_e32 v18, 16, v33
	v_and_b32_e32 v19, 0xffff0000, v33
	v_pk_fma_f32 v[2:3], v[2:3], v[62:63], v[18:19] op_sel_hi:[1,0,1]
	v_add_co_u32_e64 v18, s[40:41], s6, v14
	v_lshlrev_b32_e32 v16, 16, v32
	v_and_b32_e32 v17, 0xffff0000, v32
	v_addc_co_u32_e64 v19, s[40:41], 0, v15, s[40:41]
	v_pk_fma_f32 v[0:1], v[0:1], v[62:63], v[16:17] op_sel_hi:[1,0,1]
	s_mov_b32 s6, 0xb0000
	v_cvt_pk_bf16_f32 v16, v0, v1
	v_cvt_pk_bf16_f32 v17, v2, v3
	global_store_dwordx2 v[18:19], v[16:17], off
	s_waitcnt vmcnt(21)
; __device__ __forceinline__ unsigned cvt_pk_bf16(float lo, float hi) { unsigned r; asm volatile("v_cvt_pk_bf16_f32 %0, %1, %2" : "=v"(r) : "v"(lo), "v"(hi)); return r; }
; __device__ __forceinline__ float bf_lo(unsigned w) { return __uint_as_float(w << 16); }
; __device__ __forceinline__ float bf_hi(unsigned w) { return __uint_as_float(w & 0xffff0000u); }
; __global__ void __launch_bounds__(NTHR, 2) fwd_kernel(Args a) {
;     ...
; #pragma unroll
;                 for (int i = 0; i < 16; ++i) { u32x2 w; w.x = cvt_pk_bf16(S.x, S.y); w.y = cvt_pk_bf16(S.z, S.w); *(u32x2*)(sp + (size_t)(c0 + i) * (DK * DV)) = w;
;                     S = S * ee[i] + (f32x4){bf_lo(uu[i].x), bf_hi(uu[i].x), bf_lo(uu[i].y), bf_hi(uu[i].y)}; } }
;             *(f32x4*)(out + O_GP + ((size_t)l * 16 + bh) * (DK * DV) + k * DV + 4 * dq) = S; } }
	v_lshlrev_b32_e32 v18, 16, v35
	v_and_b32_e32 v19, 0xffff0000, v35
	v_pk_fma_f32 v[2:3], v[2:3], v[64:65], v[18:19] op_sel_hi:[1,0,1]
	v_add_co_u32_e64 v18, s[40:41], s6, v14
	v_lshlrev_b32_e32 v16, 16, v34
	v_and_b32_e32 v17, 0xffff0000, v34
	v_addc_co_u32_e64 v19, s[40:41], 0, v15, s[40:41]
	v_pk_fma_f32 v[0:1], v[0:1], v[64:65], v[16:17] op_sel_hi:[1,0,1]
	s_mov_b32 s6, 0xc0000
	v_cvt_pk_bf16_f32 v16, v0, v1
	v_cvt_pk_bf16_f32 v17, v2, v3
	global_store_dwordx2 v[18:19], v[16:17], off
	s_waitcnt vmcnt(21)
	v_lshlrev_b32_e32 v18, 16, v39
	v_and_b32_e32 v19, 0xffff0000, v39
	s_waitcnt vmcnt(20)
	v_pk_fma_f32 v[2:3], v[2:3], v[66:67], v[18:19] op_sel_hi:[1,0,1]
	v_add_co_u32_e64 v18, s[40:41], s6, v14
	v_lshlrev_b32_e32 v16, 16, v38
	v_and_b32_e32 v17, 0xffff0000, v38
	v_addc_co_u32_e64 v19, s[40:41], 0, v15, s[40:41]
	v_pk_fma_f32 v[0:1], v[0:1], v[66:67], v[16:17] op_sel_hi:[1,0,1]
	s_mov_b32 s6, 0xd0000
	v_cvt_pk_bf16_f32 v16, v0, v1
	v_cvt_pk_bf16_f32 v17, v2, v3
	global_store_dwordx2 v[18:19], v[16:17], off
	s_waitcnt vmcnt(20)
	v_lshlrev_b32_e32 v18, 16, v43
	v_and_b32_e32 v19, 0xffff0000, v43
	s_waitcnt vmcnt(19)
	v_pk_fma_f32 v[2:3], v[2:3], v[68:69], v[18:19] op_sel_hi:[1,0,1]
	v_add_co_u32_e64 v18, s[40:41], s6, v14
	v_lshlrev_b32_e32 v16, 16, v42
	v_and_b32_e32 v17, 0xffff0000, v42
	v_addc_co_u32_e64 v19, s[40:41], 0, v15, s[40:41]
	v_pk_fma_f32 v[0:1], v[0:1], v[68:69], v[16:17] op_sel_hi:[1,0,1]
	s_mov_b32 s6, 0xe0000
	v_cvt_pk_bf16_f32 v16, v0, v1
	v_cvt_pk_bf16_f32 v17, v2, v3
	global_store_dwordx2 v[18:19], v[16:17], off
	s_waitcnt vmcnt(16)
	v_lshlrev_b32_e32 v18, 16, v47
	v_and_b32_e32 v19, 0xffff0000, v47
	v_lshlrev_b32_e32 v16, 16, v46
	v_and_b32_e32 v17, 0xffff0000, v46
	v_pk_fma_f32 v[2:3], v[2:3], v[74:75], v[18:19] op_sel_hi:[1,0,1]
	v_add_co_u32_e64 v18, s[40:41], s6, v14
	v_pk_fma_f32 v[0:1], v[0:1], v[74:75], v[16:17] op_sel_hi:[1,0,1]
	s_nop 0
	v_addc_co_u32_e64 v19, s[40:41], 0, v15, s[40:41]
	v_cvt_pk_bf16_f32 v16, v0, v1
	v_cvt_pk_bf16_f32 v17, v2, v3
	s_mov_b32 s6, 0xf0000
	global_store_dwordx2 v[18:19], v[16:17], off
	s_waitcnt vmcnt(16)
	v_lshlrev_b32_e32 v16, 16, v50
	v_and_b32_e32 v17, 0xffff0000, v50
	v_lshlrev_b32_e32 v18, 16, v51
	v_and_b32_e32 v19, 0xffff0000, v51
	v_add_co_u32_e64 v14, s[40:41], s6, v14
	v_pk_fma_f32 v[2:3], v[2:3], v[76:77], v[18:19] op_sel_hi:[1,0,1]
	v_pk_fma_f32 v[0:1], v[0:1], v[76:77], v[16:17] op_sel_hi:[1,0,1]
	v_addc_co_u32_e64 v15, s[40:41], 0, v15, s[40:41]
	v_cvt_pk_bf16_f32 v16, v0, v1
	v_cvt_pk_bf16_f32 v17, v2, v3
	v_cmp_ne_u32_e32 vcc, 1, v9
	global_store_dwordx2 v[14:15], v[16:17], off
	s_waitcnt vmcnt(16)
	v_lshlrev_b32_e32 v14, 16, v70
	v_and_b32_e32 v15, 0xffff0000, v70
	v_lshlrev_b32_e32 v16, 16, v71
	v_and_b32_e32 v17, 0xffff0000, v71
	v_pk_fma_f32 v[2:3], v[2:3], v[78:79], v[16:17] op_sel_hi:[1,0,1]
	v_pk_fma_f32 v[0:1], v[0:1], v[78:79], v[14:15] op_sel_hi:[1,0,1]
	s_mov_b64 s[34:35], 0
	s_mov_b32 s7, 16
	s_cbranch_vccz .LBB0_431
	s_load_dwordx2 s[6:7], s[2:3], 0x90
	v_lshl_add_u64 v[4:5], v[4:5], 0, s[22:23]
	v_lshlrev_b64 v[4:5], 17, v[4:5]
	v_lshlrev_b32_e32 v168, 2, v6
	v_add_u32_e32 v7, s76, v7
	s_waitcnt lgkmcnt(0)
	v_lshl_add_u64 v[4:5], s[6:7], 0, v[4:5]
	v_lshl_add_u64 v[4:5], v[4:5], 0, v[168:169]
	v_lshlrev_b32_e32 v168, 2, v8
	v_lshl_add_u64 v[4:5], v[4:5], 0, v[168:169]
	v_add_co_u32_e32 v4, vcc, 0x4110000, v4
	s_mov_b32 s6, 0x1ffff
	s_nop 0
	v_addc_co_u32_e32 v5, vcc, 0, v5, vcc
	v_cmp_lt_i32_e32 vcc, s6, v7
	s_or_b64 s[28:29], vcc, s[28:29]
	global_store_dwordx4 v[4:5], v[0:3], off
	s_andn2_b64 exec, exec, s[28:29]
	s_cbranch_execnz .LBB0_430
